# row loops of phase 0 / phase 5: loop-top vmcnt waits removed (early exits drain instead); on top of the phase-2 stagger
# baseline (speedup 1.0000x reference)
.LBB0_5:
	s_or_b64 exec, exec, s[4:5]
	v_mov_b32_e32 v1, v180
	s_lshl_b32 s95, s2, 3
	v_ashrrev_i32_e32 v2, 6, v1
	v_add_u32_e32 v76, s95, v2
	s_mov_b32 s3, 0x8000
	s_lshl_b32 s33, s18, 3
	v_cmp_gt_i32_e32 vcc, s3, v76
	s_mul_i32 s52, s18, 24
	s_and_saveexec_b64 s[4:5], vcc
	s_cbranch_execz .LBB0_12
	v_lshlrev_b32_e32 v2, 4, v1
	v_and_b32_e32 v20, 0x3f0, v2
	v_lshlrev_b32_e32 v18, 2, v20
	global_load_dwordx4 v[2:5], v18, s[38:39]
	global_load_dwordx4 v[6:9], v18, s[38:39] offset:16
	global_load_dwordx4 v[10:13], v18, s[38:39] offset:32
	global_load_dwordx4 v[14:17], v18, s[38:39] offset:48
	v_mov_b32_e32 v19, 0
	v_lshlrev_b32_e32 v20, 1, v20
	v_mov_b32_e32 v21, v19
	s_add_i32 s13, s33, s33
	v_lshl_add_u64 v[66:67], s[34:35], 0, v[20:21]
	v_lshl_add_u64 v[68:69], s[36:37], 0, v[18:19]
	s_lshl_b32 s10, s18, 4
	s_mov_b64 s[6:7], 0
	s_movk_i32 s11, 0x7fff
	v_mov_b32_e32 v78, 0x358637bd
	s_mov_b32 s12, 0x800000
	s_add_i32 s13, s13, s33
	s_branch .LBB0_8
.Lp0_drain:
	s_waitcnt vmcnt(0)
.LBB0_7:
	s_or_b64 exec, exec, s[8:9]
	v_add_u32_e32 v76, s13, v70
	v_cmp_lt_i32_e32 vcc, s11, v76
	s_or_b64 s[6:7], vcc, s[6:7]
	s_andn2_b64 exec, exec, s[6:7]
	s_cbranch_execz .LBB0_12
.LBB0_8:
	v_ashrrev_i32_e32 v77, 31, v76
	v_lshlrev_b64 v[18:19], 12, v[76:77]
	v_lshl_add_u64 v[18:19], v[68:69], 0, v[18:19]
	global_load_dwordx4 v[80:83], v[18:19], off
	global_load_dwordx4 v[84:87], v[18:19], off offset:16
	global_load_dwordx4 v[88:91], v[18:19], off offset:32
	global_load_dwordx4 v[92:95], v[18:19], off offset:48
	v_add_u32_e32 v70, s33, v76
	v_add_u32_e32 v74, s10, v76
	v_add_u32_e32 v72, s52, v76
	v_min_i32_e32 v18, 0x7fff, v70
	v_min_i32_e32 v20, 0x7fff, v74
	v_min_i32_e32 v22, 0x7fff, v72
	v_ashrrev_i32_e32 v19, 31, v18
	v_ashrrev_i32_e32 v21, 31, v20
	v_ashrrev_i32_e32 v23, 31, v22
	v_lshlrev_b64 v[18:19], 12, v[18:19]
	v_lshlrev_b64 v[20:21], 12, v[20:21]
	v_lshlrev_b64 v[22:23], 12, v[22:23]
	v_lshl_add_u64 v[18:19], v[68:69], 0, v[18:19]
	v_lshl_add_u64 v[20:21], v[68:69], 0, v[20:21]
	v_lshl_add_u64 v[30:31], v[68:69], 0, v[22:23]
	global_load_dwordx4 v[50:53], v[18:19], off offset:48
	global_load_dwordx4 v[54:57], v[18:19], off offset:32
	global_load_dwordx4 v[58:61], v[18:19], off offset:16
	global_load_dwordx4 v[62:65], v[18:19], off
	global_load_dwordx4 v[34:37], v[20:21], off offset:48
	global_load_dwordx4 v[38:41], v[20:21], off offset:32
	global_load_dwordx4 v[42:45], v[20:21], off offset:16
	global_load_dwordx4 v[46:49], v[20:21], off
	s_nop 0
	global_load_dwordx4 v[18:21], v[30:31], off offset:48
	global_load_dwordx4 v[22:25], v[30:31], off offset:32
	global_load_dwordx4 v[26:29], v[30:31], off offset:16
	s_nop 0
	global_load_dwordx4 v[30:33], v[30:31], off
	v_lshlrev_b64 v[76:77], 11, v[76:77]
	v_lshl_add_u64 v[76:77], v[66:67], 0, v[76:77]
	s_waitcnt vmcnt(15)
	v_mov_b32_e32 v98, v81
	s_waitcnt vmcnt(14)
	v_mov_b32_e32 v99, v85
	v_mov_b32_e32 v96, v80
	v_mov_b32_e32 v97, v84
	s_waitcnt vmcnt(13)
	v_mov_b32_e32 v104, v89
	s_waitcnt vmcnt(12)
	v_mov_b32_e32 v105, v93
	v_pk_mul_f32 v[98:99], v[98:99], v[98:99]
	v_mov_b32_e32 v100, v82
	v_mov_b32_e32 v101, v86
	v_mov_b32_e32 v102, v88
	v_mov_b32_e32 v103, v92
	v_pk_mul_f32 v[104:105], v[104:105], v[104:105]
	v_pk_fma_f32 v[96:97], v[96:97], v[96:97], v[98:99]
	v_mov_b32_e32 v106, v83
	v_mov_b32_e32 v107, v87
	v_mov_b32_e32 v108, v90
	v_mov_b32_e32 v109, v94
	v_pk_fma_f32 v[98:99], v[102:103], v[102:103], v[104:105]
	v_pk_fma_f32 v[96:97], v[100:101], v[100:101], v[96:97]
	v_mov_b32_e32 v110, v91
	v_mov_b32_e32 v111, v95
	v_pk_fma_f32 v[98:99], v[108:109], v[108:109], v[98:99]
	v_pk_fma_f32 v[96:97], v[106:107], v[106:107], v[96:97]
	v_pk_fma_f32 v[98:99], v[110:111], v[110:111], v[98:99]
	v_add_f32_e32 v71, v96, v97
	v_add_f32_e32 v71, v71, v98
	v_add_f32_e32 v71, v71, v99
	s_nop 1
	v_add_f32_dpp v71, v71, v71 quad_perm:[1,0,3,2] row_mask:0xf bank_mask:0xf bound_ctrl:1
	s_nop 1
	v_add_f32_dpp v71, v71, v71 quad_perm:[2,3,0,1] row_mask:0xf bank_mask:0xf bound_ctrl:1
	s_nop 1
	v_add_f32_dpp v71, v71, v71 row_half_mirror row_mask:0xf bank_mask:0xf bound_ctrl:1
	s_nop 1
	v_add_f32_dpp v71, v71, v71 row_mirror row_mask:0xf bank_mask:0xf bound_ctrl:1
	s_nop 0
	v_readlane_b32 s14, v71, 16
	v_readlane_b32 s15, v71, 48
	v_readlane_b32 s8, v71, 0
	v_readlane_b32 s9, v71, 32
	v_mov_b32_e32 v96, s14
	v_mov_b32_e32 v97, s15
	v_pk_add_f32 v[96:97], s[8:9], v[96:97]
	s_nop 0
	v_add_f32_e32 v71, v96, v97
	v_fmamk_f32 v71, v71, 0x3a800000, v78
	v_mul_f32_e32 v73, 0x4b800000, v71
	v_cmp_gt_f32_e32 vcc, s12, v71
	s_nop 1
	v_cndmask_b32_e32 v71, v71, v73, vcc
	v_rsq_f32_e32 v71, v71
	s_nop 0
	v_mul_f32_e32 v73, 0x45800000, v71
	v_cndmask_b32_e32 v71, v71, v73, vcc
	v_mul_f32_e32 v73, v80, v71
	v_mul_f32_e32 v75, v81, v71
	v_mul_f32_e32 v79, v82, v71
	v_mul_f32_e32 v80, v83, v71
	v_mul_f32_e32 v81, v84, v71
	v_mul_f32_e32 v82, v85, v71
	v_mul_f32_e32 v83, v86, v71
	v_mul_f32_e32 v84, v87, v71
	v_mul_f32_e32 v85, v88, v71
	v_mul_f32_e32 v87, v90, v71
	v_mul_f32_e32 v73, v2, v73
	v_mul_f32_e32 v86, v89, v71
	v_mul_f32_e32 v88, v91, v71
	v_mul_f32_e32 v89, v92, v71
	v_mul_f32_e32 v75, v3, v75
	v_mul_f32_e32 v92, v5, v80
	v_mul_f32_e32 v82, v7, v82
	v_mul_f32_e32 v83, v8, v83
	v_mul_f32_e32 v84, v9, v84
	v_mul_f32_e32 v85, v10, v85
	v_cvt_pk_bf16_f32 v80, v73, v75
	v_mul_f32_e32 v73, v12, v87
	v_mul_f32_e32 v90, v93, v71
	v_mul_f32_e32 v91, v94, v71
	v_mul_f32_e32 v71, v95, v71
	v_mul_f32_e32 v79, v4, v79
	v_mul_f32_e32 v93, v6, v81
	v_mul_f32_e32 v86, v11, v86
	v_cvt_pk_bf16_f32 v81, v79, v92
	v_cvt_pk_bf16_f32 v82, v93, v82
	v_cvt_pk_bf16_f32 v83, v83, v84
	v_mul_f32_e32 v75, v13, v88
	v_cvt_pk_bf16_f32 v84, v85, v86
	v_cvt_pk_bf16_f32 v85, v73, v75
	v_mul_f32_e32 v73, v14, v89
	v_cmp_gt_i32_e32 vcc, s3, v70
	v_mul_f32_e32 v75, v15, v90
	v_cvt_pk_bf16_f32 v86, v73, v75
	v_mul_f32_e32 v73, v16, v91
	v_mul_f32_e32 v71, v17, v71
	v_cvt_pk_bf16_f32 v87, v73, v71
	global_store_dwordx4 v[76:77], v[80:83], off
	global_store_dwordx4 v[76:77], v[84:87], off offset:16
	s_and_saveexec_b64 s[8:9], vcc
	s_cbranch_execz .Lp0_drain
	s_waitcnt vmcnt(10)
	v_mov_b32_e32 v80, v63
	v_mov_b32_e32 v81, v59
	v_mov_b32_e32 v76, v62
	v_mov_b32_e32 v77, v58
	v_pk_mul_f32 v[80:81], v[80:81], v[80:81]
	v_mov_b32_e32 v82, v55
	v_pk_fma_f32 v[76:77], v[76:77], v[76:77], v[80:81]
	v_mov_b32_e32 v80, v64
	v_mov_b32_e32 v81, v60
	v_pk_fma_f32 v[76:77], v[80:81], v[80:81], v[76:77]
	v_mov_b32_e32 v80, v65
	v_mov_b32_e32 v81, v61
	v_mov_b32_e32 v83, v51
	v_pk_fma_f32 v[76:77], v[80:81], v[80:81], v[76:77]
	v_mov_b32_e32 v80, v54
	v_mov_b32_e32 v81, v50
	v_pk_mul_f32 v[82:83], v[82:83], v[82:83]
	v_add_f32_e32 v71, v76, v77
	v_pk_fma_f32 v[80:81], v[80:81], v[80:81], v[82:83]
	v_mov_b32_e32 v82, v56
	v_mov_b32_e32 v83, v52
	v_pk_fma_f32 v[80:81], v[82:83], v[82:83], v[80:81]
	v_mov_b32_e32 v82, v57
	v_mov_b32_e32 v83, v53
	v_pk_fma_f32 v[80:81], v[82:83], v[82:83], v[80:81]
	s_nop 0
	v_add_f32_e32 v71, v71, v80
	v_add_f32_e32 v71, v71, v81
	s_nop 1
	v_add_f32_dpp v71, v71, v71 quad_perm:[1,0,3,2] row_mask:0xf bank_mask:0xf bound_ctrl:1
	s_nop 1
	v_add_f32_dpp v71, v71, v71 quad_perm:[2,3,0,1] row_mask:0xf bank_mask:0xf bound_ctrl:1
	s_nop 1
	v_add_f32_dpp v71, v71, v71 row_half_mirror row_mask:0xf bank_mask:0xf bound_ctrl:1
	s_nop 1
	v_add_f32_dpp v71, v71, v71 row_mirror row_mask:0xf bank_mask:0xf bound_ctrl:1
	s_nop 0
	v_readlane_b32 s16, v71, 16
	v_readlane_b32 s17, v71, 48
	v_readlane_b32 s14, v71, 0
	v_readlane_b32 s15, v71, 32
	v_mov_b32_e32 v76, s16
	v_mov_b32_e32 v77, s17
	v_pk_add_f32 v[76:77], s[14:15], v[76:77]
	s_nop 0
	v_add_f32_e32 v71, v76, v77
	v_fmamk_f32 v71, v71, 0x3a800000, v78
	v_mul_f32_e32 v73, 0x4b800000, v71
	v_cmp_gt_f32_e32 vcc, s12, v71
	s_nop 1
	v_cndmask_b32_e32 v71, v71, v73, vcc
	v_rsq_f32_e32 v71, v71
	s_nop 0
	v_mul_f32_e32 v73, 0x45800000, v71
	v_cndmask_b32_e32 v71, v71, v73, vcc
	v_mul_f32_e32 v50, v50, v71
	v_mul_f32_e32 v73, v14, v50
	v_mul_f32_e32 v50, v51, v71
	v_mul_f32_e32 v75, v15, v50
	v_mul_f32_e32 v50, v52, v71
	v_mul_f32_e32 v54, v54, v71
	v_mul_f32_e32 v55, v55, v71
	v_mul_f32_e32 v56, v56, v71
	v_mul_f32_e32 v57, v57, v71
	v_mul_f32_e32 v76, v16, v50
	v_mul_f32_e32 v50, v53, v71
	v_mul_f32_e32 v62, v62, v71
	v_mul_f32_e32 v63, v63, v71
	v_mul_f32_e32 v64, v64, v71
	v_mul_f32_e32 v65, v65, v71
	v_mul_f32_e32 v58, v58, v71
	v_mul_f32_e32 v59, v59, v71
	v_mul_f32_e32 v60, v60, v71
	v_mul_f32_e32 v61, v61, v71
	v_mul_f32_e32 v54, v10, v54
	v_mul_f32_e32 v55, v11, v55
	v_mul_f32_e32 v56, v12, v56
	v_mul_f32_e32 v57, v13, v57
	v_mul_f32_e32 v71, v17, v50
	v_mul_f32_e32 v62, v2, v62
	v_mul_f32_e32 v63, v3, v63
	v_mul_f32_e32 v64, v4, v64
	v_mul_f32_e32 v65, v5, v65
	v_mul_f32_e32 v58, v6, v58
	v_mul_f32_e32 v59, v7, v59
	v_mul_f32_e32 v60, v8, v60
	v_mul_f32_e32 v61, v9, v61
	v_cvt_pk_bf16_f32 v50, v62, v63
	v_cvt_pk_bf16_f32 v51, v64, v65
	v_cvt_pk_bf16_f32 v52, v58, v59
	v_cvt_pk_bf16_f32 v53, v60, v61
	v_cvt_pk_bf16_f32 v54, v54, v55
	v_cvt_pk_bf16_f32 v55, v56, v57
	v_cvt_pk_bf16_f32 v56, v73, v75
	v_cvt_pk_bf16_f32 v57, v76, v71
	v_ashrrev_i32_e32 v71, 31, v70
	v_lshlrev_b64 v[58:59], 11, v[70:71]
	v_lshl_add_u64 v[58:59], v[66:67], 0, v[58:59]
	v_cmp_gt_i32_e32 vcc, s3, v74
	global_store_dwordx4 v[58:59], v[50:53], off
	global_store_dwordx4 v[58:59], v[54:57], off offset:16
	s_and_b64 exec, exec, vcc
	s_cbranch_execz .Lp0_drain
	s_waitcnt vmcnt(8)
	v_mov_b32_e32 v52, v47
	v_mov_b32_e32 v53, v43
	v_mov_b32_e32 v50, v46
	v_mov_b32_e32 v51, v42
	v_pk_mul_f32 v[52:53], v[52:53], v[52:53]
	v_mov_b32_e32 v54, v39
	v_pk_fma_f32 v[50:51], v[50:51], v[50:51], v[52:53]
	v_mov_b32_e32 v52, v48
	v_mov_b32_e32 v53, v44
	v_pk_fma_f32 v[50:51], v[52:53], v[52:53], v[50:51]
	v_mov_b32_e32 v52, v49
	v_mov_b32_e32 v53, v45
	v_mov_b32_e32 v55, v35
	v_pk_fma_f32 v[50:51], v[52:53], v[52:53], v[50:51]
	v_mov_b32_e32 v52, v38
	v_mov_b32_e32 v53, v34
	v_pk_mul_f32 v[54:55], v[54:55], v[54:55]
	v_add_f32_e32 v50, v50, v51
	v_pk_fma_f32 v[52:53], v[52:53], v[52:53], v[54:55]
	v_mov_b32_e32 v54, v40
	v_mov_b32_e32 v55, v36
	v_pk_fma_f32 v[52:53], v[54:55], v[54:55], v[52:53]
	v_mov_b32_e32 v54, v41
	v_mov_b32_e32 v55, v37
	v_pk_fma_f32 v[52:53], v[54:55], v[54:55], v[52:53]
	v_ashrrev_i32_e32 v75, 31, v74
	v_add_f32_e32 v50, v50, v52
	v_add_f32_e32 v50, v50, v53
	s_nop 1
	v_add_f32_dpp v50, v50, v50 quad_perm:[1,0,3,2] row_mask:0xf bank_mask:0xf bound_ctrl:1
	s_nop 1
	v_add_f32_dpp v50, v50, v50 quad_perm:[2,3,0,1] row_mask:0xf bank_mask:0xf bound_ctrl:1
	s_nop 1
	v_add_f32_dpp v50, v50, v50 row_half_mirror row_mask:0xf bank_mask:0xf bound_ctrl:1
	s_nop 1
	v_add_f32_dpp v50, v50, v50 row_mirror row_mask:0xf bank_mask:0xf bound_ctrl:1
	s_nop 0
	v_readlane_b32 s16, v50, 16
	v_readlane_b32 s17, v50, 48
	v_readlane_b32 s14, v50, 0
	v_readlane_b32 s15, v50, 32
	v_mov_b32_e32 v50, s16
	v_mov_b32_e32 v51, s17
	v_pk_add_f32 v[50:51], s[14:15], v[50:51]
	s_nop 0
	v_add_f32_e32 v50, v50, v51
	v_fmamk_f32 v50, v50, 0x3a800000, v78
	v_mul_f32_e32 v51, 0x4b800000, v50
	v_cmp_gt_f32_e32 vcc, s12, v50
	s_nop 1
	v_cndmask_b32_e32 v50, v50, v51, vcc
	v_rsq_f32_e32 v50, v50
	s_nop 0
	v_mul_f32_e32 v51, 0x45800000, v50
	v_cndmask_b32_e32 v50, v50, v51, vcc
	v_mul_f32_e32 v34, v34, v50
	v_mul_f32_e32 v51, v14, v34
	v_mul_f32_e32 v34, v35, v50
	v_mul_f32_e32 v42, v42, v50
	v_mul_f32_e32 v43, v43, v50
	v_mul_f32_e32 v52, v15, v34
	v_mul_f32_e32 v34, v36, v50
	v_mul_f32_e32 v46, v46, v50
	v_mul_f32_e32 v47, v47, v50
	v_mul_f32_e32 v48, v48, v50
	v_mul_f32_e32 v49, v49, v50
	v_mul_f32_e32 v42, v6, v42
	v_mul_f32_e32 v43, v7, v43
	v_mul_f32_e32 v53, v16, v34
	v_mul_f32_e32 v34, v37, v50
	v_mul_f32_e32 v46, v2, v46
	v_mul_f32_e32 v47, v3, v47
	v_mul_f32_e32 v48, v4, v48
	v_mul_f32_e32 v49, v5, v49
	v_mul_f32_e32 v44, v44, v50
	v_mul_f32_e32 v45, v45, v50
	v_mul_f32_e32 v38, v38, v50
	v_mul_f32_e32 v39, v39, v50
	v_mul_f32_e32 v40, v40, v50
	v_mul_f32_e32 v41, v41, v50
	v_mul_f32_e32 v50, v17, v34
	v_cvt_pk_bf16_f32 v34, v46, v47
	v_cvt_pk_bf16_f32 v35, v48, v49
	v_cvt_pk_bf16_f32 v36, v42, v43
	v_lshlrev_b64 v[42:43], 11, v[74:75]
	v_mul_f32_e32 v44, v8, v44
	v_mul_f32_e32 v45, v9, v45
	v_mul_f32_e32 v38, v10, v38
	v_mul_f32_e32 v39, v11, v39
	v_mul_f32_e32 v40, v12, v40
	v_mul_f32_e32 v41, v13, v41
	v_cvt_pk_bf16_f32 v37, v44, v45
	v_lshl_add_u64 v[42:43], v[66:67], 0, v[42:43]
	v_cmp_gt_i32_e32 vcc, s3, v72
	v_cvt_pk_bf16_f32 v38, v38, v39
	v_cvt_pk_bf16_f32 v39, v40, v41
	v_cvt_pk_bf16_f32 v40, v51, v52
	v_cvt_pk_bf16_f32 v41, v53, v50
	global_store_dwordx4 v[42:43], v[34:37], off
	global_store_dwordx4 v[42:43], v[38:41], off offset:16
	s_and_b64 exec, exec, vcc
	s_cbranch_execz .Lp0_drain
	s_waitcnt vmcnt(6)
	v_mov_b32_e32 v36, v31
	v_mov_b32_e32 v37, v27
	v_mov_b32_e32 v34, v30
	v_mov_b32_e32 v35, v26
	v_pk_mul_f32 v[36:37], v[36:37], v[36:37]
	v_mov_b32_e32 v38, v23
	v_pk_fma_f32 v[34:35], v[34:35], v[34:35], v[36:37]
	v_mov_b32_e32 v36, v32
	v_mov_b32_e32 v37, v28
	v_pk_fma_f32 v[34:35], v[36:37], v[36:37], v[34:35]
	v_mov_b32_e32 v36, v33
	v_mov_b32_e32 v37, v29
	v_mov_b32_e32 v39, v19
	v_pk_fma_f32 v[34:35], v[36:37], v[36:37], v[34:35]
	v_mov_b32_e32 v36, v22
	v_mov_b32_e32 v37, v18
	v_pk_mul_f32 v[38:39], v[38:39], v[38:39]
	v_add_f32_e32 v34, v34, v35
	v_pk_fma_f32 v[36:37], v[36:37], v[36:37], v[38:39]
	v_mov_b32_e32 v38, v24
	v_mov_b32_e32 v39, v20
	v_pk_fma_f32 v[36:37], v[38:39], v[38:39], v[36:37]
	v_mov_b32_e32 v38, v25
	v_mov_b32_e32 v39, v21
	v_pk_fma_f32 v[36:37], v[38:39], v[38:39], v[36:37]
	v_ashrrev_i32_e32 v73, 31, v72
	v_add_f32_e32 v34, v34, v36
	v_add_f32_e32 v34, v34, v37
	s_nop 1
	v_add_f32_dpp v34, v34, v34 quad_perm:[1,0,3,2] row_mask:0xf bank_mask:0xf bound_ctrl:1
	s_nop 1
	v_add_f32_dpp v34, v34, v34 quad_perm:[2,3,0,1] row_mask:0xf bank_mask:0xf bound_ctrl:1
	s_nop 1
	v_add_f32_dpp v34, v34, v34 row_half_mirror row_mask:0xf bank_mask:0xf bound_ctrl:1
	s_nop 1
	v_add_f32_dpp v34, v34, v34 row_mirror row_mask:0xf bank_mask:0xf bound_ctrl:1
	s_nop 0
	v_readlane_b32 s16, v34, 16
	v_readlane_b32 s17, v34, 48
	v_readlane_b32 s14, v34, 0
	v_readlane_b32 s15, v34, 32
	v_mov_b32_e32 v34, s16
	v_mov_b32_e32 v35, s17
	v_pk_add_f32 v[34:35], s[14:15], v[34:35]
	s_nop 0
	v_add_f32_e32 v34, v34, v35
	v_fmamk_f32 v34, v34, 0x3a800000, v78
	v_mul_f32_e32 v35, 0x4b800000, v34
	v_cmp_gt_f32_e32 vcc, s12, v34
	s_nop 1
	v_cndmask_b32_e32 v34, v34, v35, vcc
	v_rsq_f32_e32 v34, v34
	s_nop 0
	v_mul_f32_e32 v35, 0x45800000, v34
	v_cndmask_b32_e32 v34, v34, v35, vcc
	v_mul_f32_e32 v18, v18, v34
	v_mul_f32_e32 v35, v14, v18
	v_mul_f32_e32 v18, v19, v34
	v_mul_f32_e32 v26, v26, v34
	v_mul_f32_e32 v27, v27, v34
	v_mul_f32_e32 v36, v15, v18
	v_mul_f32_e32 v18, v20, v34
	v_mul_f32_e32 v30, v30, v34
	v_mul_f32_e32 v31, v31, v34
	v_mul_f32_e32 v32, v32, v34
	v_mul_f32_e32 v33, v33, v34
	v_mul_f32_e32 v26, v6, v26
	v_mul_f32_e32 v27, v7, v27
	v_mul_f32_e32 v37, v16, v18
	v_mul_f32_e32 v18, v21, v34
	v_mul_f32_e32 v30, v2, v30
	v_mul_f32_e32 v31, v3, v31
	v_mul_f32_e32 v32, v4, v32
	v_mul_f32_e32 v33, v5, v33
	v_mul_f32_e32 v28, v28, v34
	v_mul_f32_e32 v29, v29, v34
	v_mul_f32_e32 v22, v22, v34
	v_mul_f32_e32 v23, v23, v34
	v_mul_f32_e32 v24, v24, v34
	v_mul_f32_e32 v25, v25, v34
	v_mul_f32_e32 v34, v17, v18
	v_cvt_pk_bf16_f32 v18, v30, v31
	v_cvt_pk_bf16_f32 v19, v32, v33
	v_cvt_pk_bf16_f32 v20, v26, v27
	v_lshlrev_b64 v[26:27], 11, v[72:73]
	v_mul_f32_e32 v28, v8, v28
	v_mul_f32_e32 v29, v9, v29
	v_mul_f32_e32 v22, v10, v22
	v_mul_f32_e32 v23, v11, v23
	v_mul_f32_e32 v24, v12, v24
	v_mul_f32_e32 v25, v13, v25
	v_cvt_pk_bf16_f32 v21, v28, v29
	v_lshl_add_u64 v[26:27], v[66:67], 0, v[26:27]
	v_cvt_pk_bf16_f32 v22, v22, v23
	v_cvt_pk_bf16_f32 v23, v24, v25
	v_cvt_pk_bf16_f32 v24, v35, v36
	v_cvt_pk_bf16_f32 v25, v37, v34
	global_store_dwordx4 v[26:27], v[18:21], off
	global_store_dwordx4 v[26:27], v[22:25], off offset:16
	s_branch .LBB0_7

.Lgs_659:
.LBB0_600:
	s_or_b64 exec, exec, s[0:1]
	s_waitcnt lgkmcnt(0)
	s_mul_i32 s14, s18, 24
	v_mov_b32_e32 v9, v180
	s_barrier
	s_mov_b32 s3, 0x8000
	v_ashrrev_i32_e32 v0, 6, v9
	v_add_u32_e32 v8, s95, v0
	v_cmp_gt_i32_e32 vcc, s3, v8
	s_and_saveexec_b64 s[0:1], vcc
	s_cbranch_execz .LBB0_607
	v_lshlrev_b32_e32 v0, 5, v9
	s_waitcnt vmcnt(4)
	v_and_b32_e32 v10, 0x1e0, v0
	global_load_dwordx4 v[0:3], v10, s[20:21]
	global_load_dwordx4 v[4:7], v10, s[20:21] offset:16
	v_lshlrev_b32_e32 v9, 3, v9
	v_and_b32_e32 v9, 0x1f8, v9
	v_lshlrev_b32_e32 v10, 2, v9
	v_mov_b32_e32 v11, 0
	v_lshl_add_u64 v[12:13], s[34:35], 0, v[10:11]
	s_mov_b64 s[4:5], 0x10220000
	v_lshlrev_b32_e32 v10, 1, v9
	v_lshl_add_u64 v[44:45], v[12:13], 0, s[4:5]
	v_lshl_add_u64 v[10:11], s[34:35], 0, v[10:11]
	s_mov_b64 s[4:5], 0x14220000
	v_lshl_add_u64 v[46:47], v[10:11], 0, s[4:5]
	s_mov_b64 s[4:5], 0x17220000
	s_add_i32 s11, s33, s33
	v_lshl_add_u64 v[48:49], v[10:11], 0, s[4:5]
	s_lshl_b32 s8, s18, 4
	s_mov_b64 s[4:5], 0
	s_movk_i32 s9, 0x7fff
	v_mov_b32_e32 v56, 0x358637bd
	s_mov_b32 s10, 0x800000
	s_add_i32 s11, s11, s33
	s_branch .LBB0_603
.Lp5_drain:
	s_waitcnt vmcnt(0)
.LBB0_602:
	s_or_b64 exec, exec, s[6:7]
	s_nop 1
	v_add_u32_e32 v8, s11, v50
	v_cmp_lt_i32_e32 vcc, s9, v8
	s_or_b64 s[4:5], vcc, s[4:5]
	s_andn2_b64 exec, exec, s[4:5]
	s_cbranch_execz .LBB0_607
.LBB0_603:
	v_ashrrev_i32_e32 v9, 31, v8
	v_lshlrev_b64 v[70:71], 10, v[8:9]
	v_lshl_add_u64 v[10:11], v[46:47], 0, v[70:71]
	global_load_dwordx4 v[58:61], v[10:11], off
	v_lshlrev_b64 v[10:11], 11, v[8:9]
	v_lshl_add_u64 v[10:11], v[44:45], 0, v[10:11]
	global_load_dwordx4 v[62:65], v[10:11], off
	global_load_dwordx4 v[66:69], v[10:11], off offset:16
	v_add_u32_e32 v50, s33, v8
	v_add_u32_e32 v54, s8, v8
	v_add_u32_e32 v52, s14, v8
	v_min_i32_e32 v8, 0x7fff, v50
	v_min_i32_e32 v10, 0x7fff, v54
	v_min_i32_e32 v12, 0x7fff, v52
	v_ashrrev_i32_e32 v9, 31, v8
	v_ashrrev_i32_e32 v11, 31, v10
	v_ashrrev_i32_e32 v13, 31, v12
	v_lshlrev_b64 v[14:15], 11, v[8:9]
	v_lshlrev_b64 v[8:9], 10, v[8:9]
	v_lshlrev_b64 v[16:17], 11, v[10:11]
	v_lshlrev_b64 v[10:11], 10, v[10:11]
	v_lshlrev_b64 v[18:19], 11, v[12:13]
	v_lshlrev_b64 v[12:13], 10, v[12:13]
	v_lshl_add_u64 v[72:73], v[44:45], 0, v[14:15]
	v_lshl_add_u64 v[74:75], v[46:47], 0, v[8:9]
	v_lshl_add_u64 v[76:77], v[44:45], 0, v[16:17]
	v_lshl_add_u64 v[78:79], v[46:47], 0, v[10:11]
	v_lshl_add_u64 v[80:81], v[44:45], 0, v[18:19]
	v_lshl_add_u64 v[82:83], v[46:47], 0, v[12:13]
	global_load_dwordx4 v[36:39], v[72:73], off
	global_load_dwordx4 v[32:35], v[72:73], off offset:16
	global_load_dwordx4 v[40:43], v[74:75], off
	global_load_dwordx4 v[20:23], v[76:77], off offset:16
	global_load_dwordx4 v[24:27], v[76:77], off
	global_load_dwordx4 v[28:31], v[78:79], off
	global_load_dwordx4 v[12:15], v[80:81], off
	global_load_dwordx4 v[8:11], v[80:81], off offset:16
	global_load_dwordx4 v[16:19], v[82:83], off
	s_waitcnt vmcnt(11)
	v_lshlrev_b32_e32 v51, 16, v58
	v_and_b32_e32 v53, 0xffff0000, v58
	s_waitcnt vmcnt(10)
	v_mul_f32_e32 v78, v63, v63
	v_lshlrev_b32_e32 v55, 16, v59
	v_and_b32_e32 v57, 0xffff0000, v59
	v_pk_mul_f32 v[58:59], v[64:65], v[64:65]
	v_fmac_f32_e32 v78, v62, v62
	v_add_f32_e32 v58, v58, v78
	s_waitcnt vmcnt(9)
	v_pk_mul_f32 v[72:73], v[66:67], v[66:67]
	v_add_f32_e32 v58, v59, v58
	v_add_f32_e32 v58, v72, v58
	v_lshlrev_b32_e32 v74, 16, v60
	v_and_b32_e32 v75, 0xffff0000, v60
	v_lshlrev_b32_e32 v76, 16, v61
	v_and_b32_e32 v77, 0xffff0000, v61
	v_pk_mul_f32 v[60:61], v[68:69], v[68:69]
	v_add_f32_e32 v58, v73, v58
	v_add_f32_e32 v58, v60, v58
	v_add_f32_e32 v58, v61, v58
	v_mul_f32_e32 v79, 0xbfb8aa3b, v51
	v_mul_f32_e32 v80, 0xbfb8aa3b, v53
	v_add_f32_dpp v58, v58, v58 quad_perm:[1,0,3,2] row_mask:0xf bank_mask:0xf bound_ctrl:1
	v_mul_f32_e32 v81, 0xbfb8aa3b, v55
	v_mul_f32_e32 v82, 0xbfb8aa3b, v57
	v_add_f32_dpp v58, v58, v58 quad_perm:[2,3,0,1] row_mask:0xf bank_mask:0xf bound_ctrl:1
	v_mul_f32_e32 v83, 0xbfb8aa3b, v74
	v_exp_f32_e32 v78, v79
	v_add_f32_dpp v58, v58, v58 row_half_mirror row_mask:0xf bank_mask:0xf bound_ctrl:1
	v_exp_f32_e32 v79, v80
	v_exp_f32_e32 v80, v81
	v_add_f32_dpp v58, v58, v58 row_mirror row_mask:0xf bank_mask:0xf bound_ctrl:1
	v_fmamk_f32 v58, v58, 0x3c000000, v56
	v_mul_f32_e32 v61, 0x4b800000, v58
	v_cmp_gt_f32_e32 vcc, s10, v58
	v_exp_f32_e32 v81, v82
	v_exp_f32_e32 v82, v83
	v_cndmask_b32_e32 v58, v58, v61, vcc
	v_rsq_f32_e32 v58, v58
	v_add_f32_e32 v59, 1.0, v78
	v_add_f32_e32 v72, 1.0, v80
	v_add_f32_e32 v73, 1.0, v81
	v_add_f32_e32 v78, 1.0, v82
	v_rcp_f32_e32 v61, v72
	v_rcp_f32_e32 v72, v73
	v_rcp_f32_e32 v73, v78
	v_mul_f32_e32 v78, 0x45800000, v58
	v_rcp_f32_e32 v59, v59
	v_cndmask_b32_e32 v58, v58, v78, vcc
	v_mul_f32_e32 v62, v62, v58
	v_add_f32_e32 v60, 1.0, v79
	v_mul_f32_e32 v62, v0, v62
	v_rcp_f32_e32 v60, v60
	v_mul_f32_e32 v51, v62, v51
	v_mul_f32_e32 v63, v63, v58
	v_mul_f32_e32 v66, v66, v58
	v_mul_f32_e32 v51, v59, v51
	v_mul_f32_e32 v59, 0xbfb8aa3b, v75
	v_mul_f32_e32 v63, v1, v63
	v_mul_f32_e32 v66, v4, v66
	v_exp_f32_e32 v59, v59
	v_mul_f32_e32 v53, v63, v53
	v_mul_f32_e32 v62, v66, v74
	v_mul_f32_e32 v53, v60, v53
	v_mul_f32_e32 v60, v73, v62
	v_mul_f32_e32 v62, 0xbfb8aa3b, v76
	v_mul_f32_e32 v64, v64, v58
	v_exp_f32_e32 v62, v62
	v_mul_f32_e32 v64, v2, v64
	v_add_f32_e32 v59, 1.0, v59
	v_mul_f32_e32 v55, v64, v55
	v_rcp_f32_e32 v59, v59
	v_mul_f32_e32 v55, v61, v55
	v_mul_f32_e32 v61, v67, v58
	v_mul_f32_e32 v61, v5, v61
	v_add_f32_e32 v62, 1.0, v62
	v_mul_f32_e32 v63, 0xbfb8aa3b, v77
	v_mul_f32_e32 v61, v61, v75
	v_rcp_f32_e32 v62, v62
	v_exp_f32_e32 v63, v63
	v_mul_f32_e32 v61, v59, v61
	v_mul_f32_e32 v59, v68, v58
	v_mul_f32_e32 v59, v6, v59
	v_mul_f32_e32 v59, v59, v76
	v_mul_f32_e32 v62, v62, v59
	v_add_f32_e32 v59, 1.0, v63
	v_rcp_f32_e32 v59, v59
	v_mul_f32_e32 v65, v65, v58
	v_mul_f32_e32 v58, v69, v58
	v_mul_f32_e32 v58, v7, v58
	v_mul_f32_e32 v65, v3, v65
	v_mul_f32_e32 v58, v58, v77
	v_mul_f32_e32 v57, v65, v57
	v_mul_f32_e32 v63, v59, v58
	v_mul_f32_e32 v57, v72, v57
	v_cvt_pk_bf16_f32 v58, v51, v53
	v_cvt_pk_bf16_f32 v59, v55, v57
	v_cvt_pk_bf16_f32 v60, v60, v61
	v_cvt_pk_bf16_f32 v61, v62, v63
	v_lshl_add_u64 v[62:63], v[48:49], 0, v[70:71]
	v_cmp_gt_i32_e32 vcc, s3, v50
	global_store_dwordx4 v[62:63], v[58:61], off
	s_and_saveexec_b64 s[6:7], vcc
	s_cbranch_execz .Lp5_drain
	s_waitcnt vmcnt(9)
	v_mul_f32_e32 v58, v37, v37
	s_waitcnt vmcnt(7)
	v_lshlrev_b32_e32 v51, 16, v40
	v_and_b32_e32 v53, 0xffff0000, v40
	v_lshlrev_b32_e32 v55, 16, v41
	v_and_b32_e32 v57, 0xffff0000, v41
	v_fmac_f32_e32 v58, v36, v36
	v_pk_mul_f32 v[40:41], v[38:39], v[38:39]
	v_lshlrev_b32_e32 v60, 16, v42
	v_add_f32_e32 v40, v40, v58
	v_add_f32_e32 v61, v41, v40
	v_pk_mul_f32 v[58:59], v[32:33], v[32:33]
	v_pk_mul_f32 v[40:41], v[34:35], v[34:35]
	v_add_f32_e32 v58, v58, v61
	v_add_f32_e32 v58, v59, v58
	v_add_f32_e32 v40, v40, v58
	v_add_f32_e32 v40, v41, v40
	v_mul_f32_e32 v59, 0xbfb8aa3b, v51
	v_exp_f32_e32 v59, v59
	v_add_f32_dpp v40, v40, v40 quad_perm:[1,0,3,2] row_mask:0xf bank_mask:0xf bound_ctrl:1
	s_nop 1
	v_add_f32_dpp v40, v40, v40 quad_perm:[2,3,0,1] row_mask:0xf bank_mask:0xf bound_ctrl:1
	s_nop 1
	v_add_f32_dpp v40, v40, v40 row_half_mirror row_mask:0xf bank_mask:0xf bound_ctrl:1
	s_nop 1
	v_add_f32_dpp v40, v40, v40 row_mirror row_mask:0xf bank_mask:0xf bound_ctrl:1
	v_fmamk_f32 v40, v40, 0x3c000000, v56
	v_mul_f32_e32 v41, 0x4b800000, v40
	v_cmp_gt_f32_e32 vcc, s10, v40
	s_nop 1
	v_cndmask_b32_e32 v40, v40, v41, vcc
	v_rsq_f32_e32 v40, v40
	v_and_b32_e32 v41, 0xffff0000, v42
	v_lshlrev_b32_e32 v42, 16, v43
	v_and_b32_e32 v43, 0xffff0000, v43
	v_mul_f32_e32 v58, 0x45800000, v40
	v_cndmask_b32_e32 v40, v40, v58, vcc
	v_mul_f32_e32 v36, v36, v40
	v_mul_f32_e32 v36, v0, v36
	v_mul_f32_e32 v36, v36, v51
	v_mul_f32_e32 v51, 0xbfb8aa3b, v53
	v_exp_f32_e32 v51, v51
	v_mul_f32_e32 v37, v37, v40
	v_mul_f32_e32 v37, v1, v37
	v_mul_f32_e32 v37, v37, v53
	v_add_f32_e32 v51, 1.0, v51
	v_mul_f32_e32 v53, 0xbfb8aa3b, v55
	v_rcp_f32_e32 v51, v51
	v_exp_f32_e32 v53, v53
	v_mul_f32_e32 v38, v38, v40
	v_mul_f32_e32 v38, v2, v38
	v_mul_f32_e32 v37, v51, v37
	v_add_f32_e32 v51, 1.0, v53
	v_mul_f32_e32 v53, 0xbfb8aa3b, v57
	v_rcp_f32_e32 v51, v51
	v_exp_f32_e32 v53, v53
	v_mul_f32_e32 v38, v38, v55
	v_mul_f32_e32 v39, v39, v40
	v_mul_f32_e32 v38, v51, v38
	v_add_f32_e32 v51, 1.0, v53
	v_mul_f32_e32 v53, 0xbfb8aa3b, v60
	v_rcp_f32_e32 v51, v51
	v_exp_f32_e32 v53, v53
	v_mul_f32_e32 v39, v3, v39
	v_mul_f32_e32 v39, v39, v57
	v_mul_f32_e32 v39, v51, v39
	v_add_f32_e32 v51, 1.0, v53
	v_mul_f32_e32 v53, 0xbfb8aa3b, v41
	v_rcp_f32_e32 v51, v51
	v_exp_f32_e32 v53, v53
	v_mul_f32_e32 v32, v32, v40
	v_mul_f32_e32 v32, v4, v32
	v_mul_f32_e32 v32, v32, v60
	v_mul_f32_e32 v51, v51, v32
	v_mul_f32_e32 v32, v33, v40
	v_add_f32_e32 v33, 1.0, v53
	v_mul_f32_e32 v53, 0xbfb8aa3b, v42
	v_rcp_f32_e32 v33, v33
	v_exp_f32_e32 v53, v53
	v_mul_f32_e32 v32, v5, v32
	v_mul_f32_e32 v32, v32, v41
	v_mul_f32_e32 v41, v33, v32
	v_mul_f32_e32 v32, v34, v40
	v_add_f32_e32 v33, 1.0, v53
	v_mul_f32_e32 v34, 0xbfb8aa3b, v43
	v_rcp_f32_e32 v33, v33
	v_exp_f32_e32 v34, v34
	v_mul_f32_e32 v32, v6, v32
	v_mul_f32_e32 v32, v32, v42
	v_add_f32_e32 v58, 1.0, v59
	v_mul_f32_e32 v42, v33, v32
	v_add_f32_e32 v32, 1.0, v34
	v_rcp_f32_e32 v58, v58
	v_rcp_f32_e32 v32, v32
	v_mul_f32_e32 v33, v35, v40
	v_mul_f32_e32 v33, v7, v33
	v_mul_f32_e32 v33, v33, v43
	v_mul_f32_e32 v36, v58, v36
	v_mul_f32_e32 v35, v32, v33
	v_cvt_pk_bf16_f32 v32, v36, v37
	v_cvt_pk_bf16_f32 v33, v38, v39
	v_cvt_pk_bf16_f32 v34, v51, v41
	v_ashrrev_i32_e32 v51, 31, v50
	v_lshlrev_b64 v[36:37], 10, v[50:51]
	v_lshl_add_u64 v[36:37], v[48:49], 0, v[36:37]
	v_cmp_gt_i32_e32 vcc, s3, v54
	v_cvt_pk_bf16_f32 v35, v42, v35
	global_store_dwordx4 v[36:37], v[32:35], off
	s_and_b64 exec, exec, vcc
	s_cbranch_execz .Lp5_drain
	s_waitcnt vmcnt(6)
	v_mul_f32_e32 v32, v25, v25
	s_waitcnt vmcnt(5)
	v_lshlrev_b32_e32 v34, 16, v28
	v_and_b32_e32 v35, 0xffff0000, v28
	v_lshlrev_b32_e32 v36, 16, v29
	v_and_b32_e32 v37, 0xffff0000, v29
	v_fmac_f32_e32 v32, v24, v24
	v_pk_mul_f32 v[28:29], v[26:27], v[26:27]
	v_lshlrev_b32_e32 v38, 16, v30
	v_add_f32_e32 v28, v28, v32
	v_add_f32_e32 v39, v29, v28
	v_pk_mul_f32 v[32:33], v[20:21], v[20:21]
	v_pk_mul_f32 v[28:29], v[22:23], v[22:23]
	v_add_f32_e32 v32, v32, v39
	v_add_f32_e32 v32, v33, v32
	v_add_f32_e32 v28, v28, v32
	v_add_f32_e32 v28, v29, v28
	v_mul_f32_e32 v33, 0xbfb8aa3b, v34
	v_exp_f32_e32 v33, v33
	v_add_f32_dpp v28, v28, v28 quad_perm:[1,0,3,2] row_mask:0xf bank_mask:0xf bound_ctrl:1
	v_ashrrev_i32_e32 v55, 31, v54
	s_nop 0
	v_add_f32_dpp v28, v28, v28 quad_perm:[2,3,0,1] row_mask:0xf bank_mask:0xf bound_ctrl:1
	s_nop 1
	v_add_f32_dpp v28, v28, v28 row_half_mirror row_mask:0xf bank_mask:0xf bound_ctrl:1
	s_nop 1
	v_add_f32_dpp v28, v28, v28 row_mirror row_mask:0xf bank_mask:0xf bound_ctrl:1
	v_fmamk_f32 v28, v28, 0x3c000000, v56
	v_mul_f32_e32 v29, 0x4b800000, v28
	v_cmp_gt_f32_e32 vcc, s10, v28
	s_nop 1
	v_cndmask_b32_e32 v28, v28, v29, vcc
	v_rsq_f32_e32 v28, v28
	v_and_b32_e32 v29, 0xffff0000, v30
	v_lshlrev_b32_e32 v30, 16, v31
	v_and_b32_e32 v31, 0xffff0000, v31
	v_mul_f32_e32 v32, 0x45800000, v28
	v_cndmask_b32_e32 v28, v28, v32, vcc
	v_add_f32_e32 v32, 1.0, v33
	v_mul_f32_e32 v33, 0xbfb8aa3b, v35
	v_rcp_f32_e32 v32, v32
	v_exp_f32_e32 v33, v33
	v_mul_f32_e32 v24, v24, v28
	v_mul_f32_e32 v24, v0, v24
	v_mul_f32_e32 v24, v24, v34
	v_mul_f32_e32 v24, v32, v24
	v_add_f32_e32 v32, 1.0, v33
	v_mul_f32_e32 v33, 0xbfb8aa3b, v36
	v_rcp_f32_e32 v32, v32
	v_exp_f32_e32 v33, v33
	v_mul_f32_e32 v25, v25, v28
	v_mul_f32_e32 v25, v1, v25
	v_mul_f32_e32 v25, v25, v35
	v_mul_f32_e32 v25, v32, v25
	v_add_f32_e32 v32, 1.0, v33
	v_mul_f32_e32 v33, 0xbfb8aa3b, v37
	v_rcp_f32_e32 v32, v32
	v_exp_f32_e32 v33, v33
	v_mul_f32_e32 v26, v26, v28
	v_mul_f32_e32 v26, v2, v26
	v_mul_f32_e32 v26, v26, v36
	v_mul_f32_e32 v26, v32, v26
	v_add_f32_e32 v32, 1.0, v33
	v_mul_f32_e32 v33, 0xbfb8aa3b, v38
	v_rcp_f32_e32 v32, v32
	v_exp_f32_e32 v33, v33
	v_mul_f32_e32 v27, v27, v28
	v_mul_f32_e32 v27, v3, v27
	v_mul_f32_e32 v27, v27, v37
	v_mul_f32_e32 v27, v32, v27
	v_add_f32_e32 v32, 1.0, v33
	v_mul_f32_e32 v33, 0xbfb8aa3b, v29
	v_rcp_f32_e32 v32, v32
	v_exp_f32_e32 v33, v33
	v_mul_f32_e32 v20, v20, v28
	v_mul_f32_e32 v20, v4, v20
	v_mul_f32_e32 v20, v20, v38
	v_mul_f32_e32 v32, v32, v20
	v_mul_f32_e32 v20, v21, v28
	v_add_f32_e32 v21, 1.0, v33
	v_mul_f32_e32 v33, 0xbfb8aa3b, v30
	v_rcp_f32_e32 v21, v21
	v_exp_f32_e32 v33, v33
	v_mul_f32_e32 v20, v5, v20
	v_mul_f32_e32 v20, v20, v29
	v_mul_f32_e32 v29, v21, v20
	v_mul_f32_e32 v20, v22, v28
	v_add_f32_e32 v21, 1.0, v33
	v_mul_f32_e32 v22, 0xbfb8aa3b, v31
	v_rcp_f32_e32 v21, v21
	v_exp_f32_e32 v22, v22
	v_mul_f32_e32 v20, v6, v20
	v_mul_f32_e32 v20, v20, v30
	v_mul_f32_e32 v30, v21, v20
	v_add_f32_e32 v20, 1.0, v22
	v_rcp_f32_e32 v20, v20
	v_mul_f32_e32 v21, v23, v28
	v_mul_f32_e32 v21, v7, v21
	v_mul_f32_e32 v21, v21, v31
	v_mul_f32_e32 v23, v20, v21
	v_cvt_pk_bf16_f32 v20, v24, v25
	v_lshlrev_b64 v[24:25], 10, v[54:55]
	v_lshl_add_u64 v[24:25], v[48:49], 0, v[24:25]
	v_cmp_gt_i32_e32 vcc, s3, v52
	v_cvt_pk_bf16_f32 v21, v26, v27
	v_cvt_pk_bf16_f32 v22, v32, v29
	v_cvt_pk_bf16_f32 v23, v30, v23
	global_store_dwordx4 v[24:25], v[20:23], off
	s_and_b64 exec, exec, vcc
	s_cbranch_execz .Lp5_drain
	s_waitcnt vmcnt(5)
	v_mul_f32_e32 v20, v13, v13
	s_waitcnt vmcnt(3)
	v_lshlrev_b32_e32 v22, 16, v16
	v_and_b32_e32 v23, 0xffff0000, v16
	v_lshlrev_b32_e32 v24, 16, v17
	v_and_b32_e32 v25, 0xffff0000, v17
	v_fmac_f32_e32 v20, v12, v12
	v_pk_mul_f32 v[16:17], v[14:15], v[14:15]
	v_lshlrev_b32_e32 v26, 16, v18
	v_add_f32_e32 v16, v16, v20
	v_add_f32_e32 v27, v17, v16
	v_pk_mul_f32 v[20:21], v[8:9], v[8:9]
	v_pk_mul_f32 v[16:17], v[10:11], v[10:11]
	v_add_f32_e32 v20, v20, v27
	v_add_f32_e32 v20, v21, v20
	v_add_f32_e32 v16, v16, v20
	v_add_f32_e32 v16, v17, v16
	v_mul_f32_e32 v21, 0xbfb8aa3b, v22
	v_exp_f32_e32 v21, v21
	v_add_f32_dpp v16, v16, v16 quad_perm:[1,0,3,2] row_mask:0xf bank_mask:0xf bound_ctrl:1
	v_ashrrev_i32_e32 v53, 31, v52
	s_nop 0
	v_add_f32_dpp v16, v16, v16 quad_perm:[2,3,0,1] row_mask:0xf bank_mask:0xf bound_ctrl:1
	s_nop 1
	v_add_f32_dpp v16, v16, v16 row_half_mirror row_mask:0xf bank_mask:0xf bound_ctrl:1
	s_nop 1
	v_add_f32_dpp v16, v16, v16 row_mirror row_mask:0xf bank_mask:0xf bound_ctrl:1
	v_fmamk_f32 v16, v16, 0x3c000000, v56
	v_mul_f32_e32 v17, 0x4b800000, v16
	v_cmp_gt_f32_e32 vcc, s10, v16
	s_nop 1
	v_cndmask_b32_e32 v16, v16, v17, vcc
	v_rsq_f32_e32 v16, v16
	v_and_b32_e32 v17, 0xffff0000, v18
	v_lshlrev_b32_e32 v18, 16, v19
	v_and_b32_e32 v19, 0xffff0000, v19
	v_mul_f32_e32 v20, 0x45800000, v16
	v_cndmask_b32_e32 v16, v16, v20, vcc
	v_add_f32_e32 v20, 1.0, v21
	v_mul_f32_e32 v21, 0xbfb8aa3b, v23
	v_rcp_f32_e32 v20, v20
	v_exp_f32_e32 v21, v21
	v_mul_f32_e32 v12, v12, v16
	v_mul_f32_e32 v12, v0, v12
	v_mul_f32_e32 v12, v12, v22
	v_mul_f32_e32 v12, v20, v12
	v_add_f32_e32 v20, 1.0, v21
	v_mul_f32_e32 v21, 0xbfb8aa3b, v24
	v_rcp_f32_e32 v20, v20
	v_exp_f32_e32 v21, v21
	v_mul_f32_e32 v13, v13, v16
	v_mul_f32_e32 v13, v1, v13
	v_mul_f32_e32 v13, v13, v23
	v_mul_f32_e32 v13, v20, v13
	v_add_f32_e32 v20, 1.0, v21
	v_mul_f32_e32 v21, 0xbfb8aa3b, v25
	v_rcp_f32_e32 v20, v20
	v_exp_f32_e32 v21, v21
	v_mul_f32_e32 v14, v14, v16
	v_mul_f32_e32 v14, v2, v14
	v_mul_f32_e32 v14, v14, v24
	v_mul_f32_e32 v14, v20, v14
	v_add_f32_e32 v20, 1.0, v21
	v_mul_f32_e32 v21, 0xbfb8aa3b, v26
	v_rcp_f32_e32 v20, v20
	v_exp_f32_e32 v21, v21
	v_mul_f32_e32 v15, v15, v16
	v_mul_f32_e32 v15, v3, v15
	v_mul_f32_e32 v15, v15, v25
	v_mul_f32_e32 v15, v20, v15
	v_add_f32_e32 v20, 1.0, v21
	v_mul_f32_e32 v21, 0xbfb8aa3b, v17
	v_rcp_f32_e32 v20, v20
	v_exp_f32_e32 v21, v21
	v_mul_f32_e32 v8, v8, v16
	v_mul_f32_e32 v8, v4, v8
	v_mul_f32_e32 v8, v8, v26
	v_mul_f32_e32 v20, v20, v8
	v_mul_f32_e32 v8, v9, v16
	v_add_f32_e32 v9, 1.0, v21
	v_mul_f32_e32 v21, 0xbfb8aa3b, v18
	v_rcp_f32_e32 v9, v9
	v_exp_f32_e32 v21, v21
	v_mul_f32_e32 v8, v5, v8
	v_mul_f32_e32 v8, v8, v17
	v_mul_f32_e32 v17, v9, v8
	v_mul_f32_e32 v8, v10, v16
	v_add_f32_e32 v9, 1.0, v21
	v_mul_f32_e32 v10, 0xbfb8aa3b, v19
	v_rcp_f32_e32 v9, v9
	v_exp_f32_e32 v10, v10
	v_mul_f32_e32 v8, v6, v8
	v_mul_f32_e32 v8, v8, v18
	v_mul_f32_e32 v18, v9, v8
	v_add_f32_e32 v8, 1.0, v10
	v_rcp_f32_e32 v8, v8
	v_mul_f32_e32 v9, v11, v16
	v_mul_f32_e32 v9, v7, v9
	v_mul_f32_e32 v9, v9, v19
	v_mul_f32_e32 v11, v8, v9
	v_cvt_pk_bf16_f32 v8, v12, v13
	v_lshlrev_b64 v[12:13], 10, v[52:53]
	v_lshl_add_u64 v[12:13], v[48:49], 0, v[12:13]
	v_cvt_pk_bf16_f32 v9, v14, v15
	v_cvt_pk_bf16_f32 v10, v20, v17
	v_cvt_pk_bf16_f32 v11, v18, v11
	global_store_dwordx4 v[12:13], v[8:11], off
	s_branch .LBB0_602
